# PH7: ssq loads for the next unit issued inside the current epilogue; epilogue-start vmcnt(0) dropped (on v34)
# speedup vs baseline: 1.0081x; 1.0081x over previous
; #define PG8_STAGE(bufoff, gbase, voff) do { _Pragma("unroll") for (int _i = 0; _i < 2; ++_i) \
;         __builtin_amdgcn_global_load_lds((const unsigned*)((const char*)(gbase) + (voff)[_i]), (LAS unsigned*)(lds + (bufoff) + ldsw + _i * 8192), 16, 0, 0); } while (0)
; #define PG8_WAIT_V(n) asm volatile("s_waitcnt vmcnt(" #n ")" ::: "memory")
; #define PG8_BAR __builtin_amdgcn_s_barrier()
; template <class Epi>
; __device__ __forceinline__ void gemm_phase(LAS unsigned char* lds, const Gemm g, const StaticOrder& S, const Epi& E, const int wid) {
;     ...
;     PG8_STAGE(PG8_SB(0, 0), cB, voffB); PG8_STAGE(PG8_SB(0, 1), cB + hsB, voffB); PG8_STAGE(PG8_SA(0, 0), cA, voffA); PG8_STAGE(PG8_SA(0, 1), cA + hsA, voffA);
;     if (wr == 1) PG8_BAR;
;     PG8_WAIT_V(2); PG8_BAR;
;     PG8_STAGE(PG8_SB(1, 0), cB + kstep, voffB); PG8_STAGE(PG8_SA(1, 0), cA + kstep, voffA); PG8_STAGE(PG8_SB(1, 1), cB + hsB + kstep, voffB);
;     PG8_WAIT_V(6); PG8_BAR;
;     __device__ __forceinline__ void operator()(const Acc& acc, const pg8::Unit& u, int wid) const {
;     ...
;         for (int i = 0; i < 8; ++i) scv[i] = ssq ? ssq[row0 + (i >> 2) * 128 + (i & 3) * 16] : 0.f;
.LBB0_881:
	s_mov_b64 s[10:11], 0x80
	s_add_i32 m0, s76, 0x18000
	v_lshl_add_u64 v[6:7], v[6:7], 0, s[10:11]
	global_load_lds_dwordx4 v[6:7], off
	v_lshl_add_u64 v[4:5], v[4:5], 0, s[10:11]
	s_add_i32 m0, s76, 0x1a000
	s_add_i32 s81, s76, 0x8000
	s_add_i32 s82, s76, 0xa000
	global_load_lds_dwordx4 v[4:5], off
	v_lshl_add_u64 v[0:1], v[0:1], 0, s[10:11]
	s_mov_b32 m0, s81
	s_add_u32 s4, s24, 0x10080
	global_load_lds_dwordx4 v[0:1], off
	v_lshl_add_u64 v[0:1], v[2:3], 0, s[10:11]
	s_mov_b32 m0, s82
	s_addc_u32 s5, s25, 0
	global_load_lds_dwordx4 v[0:1], off
	s_add_i32 m0, s76, 0x1c000
	v_lshl_add_u64 v[0:1], s[4:5], 0, v[132:133]
	global_load_lds_dwordx4 v[0:1], off
	v_lshl_add_u64 v[0:1], s[4:5], 0, v[128:129]
	s_add_i32 m0, s76, 0x1e000
	v_and_b32_e32 v2, 48, v8
	global_load_lds_dwordx4 v[0:1], off
	s_waitcnt vmcnt(8)
	s_barrier
	v_and_b32_e32 v0, 15, v8
	v_ashrrev_i32_e32 v1, 6, v8
	v_readlane_b32 s4, v254, 3
	v_lshl_or_b32 v0, v0, 6, v2
	v_lshlrev_b32_e32 v3, 2, v8
	v_lshl_add_u32 v2, v1, 10, s4
	v_readlane_b32 s4, v254, 5
	v_and_b32_e32 v3, 32, v3
	s_waitcnt vmcnt(6)
	s_cmpk_lt_u32 s3, 0x100
	v_add_lshl_u32 v1, v1, s4, 10
	v_bitop3_b32 v2, v0, v2, v3 bitop3:0xde
	v_bitop3_b32 v146, v0, v1, v3 bitop3:0xde
	s_cselect_b64 s[16:17], -1, 0
	s_lshl_b32 s4, s33, 4
	s_add_i32 s92, 0, 0x10000
	s_add_i32 s93, 0, 0x14000
	s_sext_i32_i8 s96, s6
	s_and_b32 s83, s4, 0x3fffffc0
	s_ashr_i32 s90, s56, 31
	s_mov_b32 s91, s56
	v_mov_b64_e32 v[136:137], 0x500
	v_mov_b64_e32 v[138:139], 0x4ff
	v_add_u32_e32 v147, s92, v146
	v_add_u32_e32 v148, s93, v146
	v_add_u32_e32 v149, 0, v2
	v_mov_b32_e32 v150, 0x358637bd
	s_movk_i32 s94, 0x1400
	s_barrier
	s_mov_b32 s4, s89
	s_lshl_b32 s4, s4, 8
	s_add_i32 s4, s4, s83
	v_mbcnt_lo_u32_b32 v238, -1, 0
	v_mbcnt_hi_u32_b32 v238, -1, v238
	v_and_or_b32 v238, v238, 15, s4
	v_ashrrev_i32_e32 v239, 31, v238
	v_lshl_add_u64 v[238:239], v[238:239], 2, s[60:61]
	global_load_dword v228, v[238:239], off
	global_load_dword v229, v[238:239], off offset:64
	global_load_dword v230, v[238:239], off offset:128
	global_load_dword v231, v[238:239], off offset:192
	global_load_dword v232, v[238:239], off offset:512
	global_load_dword v233, v[238:239], off offset:576
	global_load_dword v234, v[238:239], off offset:640
	global_load_dword v235, v[238:239], off offset:704
	s_branch .LBB0_884

; __device__ __forceinline__ int lane_id_asm() { int l; asm volatile("v_mbcnt_lo_u32_b32 %0, -1, 0\n\tv_mbcnt_hi_u32_b32 %0, -1, %0" : "=v"(l)); return l; }
; __device__ __forceinline__ u32x4 pack8(f32x4 a, f32x4 b) { u32x4 w; w.x = pk2(a[0], a[1]); w.y = pk2(a[2], a[3]); w.z = pk2(b[0], b[1]); w.w = pk2(b[2], b[3]); return w; }
;     __device__ __forceinline__ void operator()(const Acc& acc, const pg8::Unit& u, int wid) const {
;         const int lane_ = lane_id_asm(), wr = wid >> 2, wc = wid & 3, fr = lane_ & 15, fq = lane_ >> 4;
;         const int row0 = u.pm * 256 + wr * 64 + fr, col0 = u.pn * 256 + wc * 32 + 8 * fq;
;         float scv[8];
; #pragma unroll
;         for (int i = 0; i < 8; ++i) scv[i] = ssq ? ssq[row0 + (i >> 2) * 128 + (i & 3) * 16] : 0.f;
; #pragma unroll
;         for (int ai = 0; ai < 2; ++ai)
; #pragma unroll
;             for (int m = 0; m < 4; ++m) {
;                 const int row = row0 + ai * 128 + m * 16;
;                 const float sc = ssq ? __builtin_amdgcn_rsqf(scv[ai * 4 + m] * inv_n + EPS) : 1.f;
; #pragma unroll
;                 for (int bj = 0; bj < 2; ++bj) {
;                     f32x4 v0 = acc[ai][bj][m][0] * sc, v1 = acc[ai][bj][m][1] * sc;
;                     if (ACT == 1) {
; #pragma unroll
;                         for (int e = 0; e < 4; ++e) { float a = fmaxf(v0[e], 0.f), b = fmaxf(v1[e], 0.f); v0[e] = a * a; v1[e] = b * b; }
;                     }
;                     *(u32x4*)(O + (size_t)row * ldc + col0 + bj * 128) = pack8(v0, v1);
.LBB0_892:
	s_lshl_b32 s4, s89, 8
	s_add_i32 s4, s4, s83
	v_mbcnt_lo_u32_b32 v151, -1, 0
	v_mbcnt_hi_u32_b32 v151, -1, v151
	v_mov_b64_e32 v[142:143], s[48:49]
	v_and_or_b32 v140, v151, 15, s4
	v_ashrrev_i32_e32 v141, 31, v140
	v_lshl_add_u64 v[144:145], v[140:141], 2, s[60:61]
	s_lshl_b32 s4, s96, 8
	v_ashrrev_i32_e32 v151, 1, v151
	s_or_b32 s4, s4, s69
	v_and_b32_e32 v151, -8, v151
	v_add_u32_e32 v152, s4, v151
	v_or_b32_e32 v151, 16, v140
	v_mad_i64_i32 v[156:157], s[4:5], v151, s94, v[142:143]
	v_or_b32_e32 v158, 32, v140
	v_ashrrev_i32_e32 v153, 31, v152
	v_mad_i64_i32 v[154:155], s[4:5], v140, s94, v[142:143]
	v_mad_i64_i32 v[158:159], s[4:5], v158, s94, v[142:143]
	v_lshlrev_b64 v[144:145], 1, v[152:153]
	v_lshl_add_u64 v[152:153], v[154:155], 0, v[144:145]
	v_lshl_add_u64 v[154:155], v[156:157], 0, v[144:145]
	v_lshl_add_u64 v[156:157], v[158:159], 0, v[144:145]
	v_add_u32_e32 v170, 0x80, v140
	s_and_b64 vcc, exec, s[6:7]
	s_mov_b64 s[6:7], -1
	s_waitcnt lgkmcnt(0)
	v_fmamk_f32 v141, v228, 0x3b800000, v150
	v_fmamk_f32 v159, v229, 0x3b800000, v150
	v_fmamk_f32 v161, v230, 0x3b800000, v150
	v_rsq_f32_e32 v158, v141
	v_fmamk_f32 v141, v231, 0x3b800000, v150
	v_rsq_f32_e32 v160, v159
	v_rsq_f32_e32 v162, v161
	v_pk_mul_f32 v[126:127], v[126:127], v[158:159] op_sel_hi:[1,0]
	v_pk_mul_f32 v[124:125], v[124:125], v[158:159] op_sel_hi:[1,0]
	v_pk_mul_f32 v[122:123], v[122:123], v[158:159] op_sel_hi:[1,0]
	v_pk_mul_f32 v[120:121], v[120:121], v[158:159] op_sel_hi:[1,0]
	v_pk_mul_f32 v[106:107], v[106:107], v[158:159] op_sel_hi:[1,0]
	v_pk_mul_f32 v[104:105], v[104:105], v[158:159] op_sel_hi:[1,0]
	v_pk_mul_f32 v[98:99], v[98:99], v[158:159] op_sel_hi:[1,0]
	v_pk_mul_f32 v[96:97], v[96:97], v[158:159] op_sel_hi:[1,0]
	v_pk_mul_f32 v[118:119], v[118:119], v[160:161] op_sel_hi:[1,0]
	v_pk_mul_f32 v[116:117], v[116:117], v[160:161] op_sel_hi:[1,0]
	v_pk_mul_f32 v[114:115], v[114:115], v[160:161] op_sel_hi:[1,0]
	v_pk_mul_f32 v[112:113], v[112:113], v[160:161] op_sel_hi:[1,0]
	v_pk_mul_f32 v[94:95], v[94:95], v[160:161] op_sel_hi:[1,0]
	v_pk_mul_f32 v[92:93], v[92:93], v[160:161] op_sel_hi:[1,0]
	v_pk_mul_f32 v[158:159], v[90:91], v[160:161] op_sel_hi:[1,0]
	v_pk_mul_f32 v[160:161], v[88:89], v[160:161] op_sel_hi:[1,0]
	v_pk_mul_f32 v[110:111], v[110:111], v[162:163] op_sel_hi:[1,0]
	v_pk_mul_f32 v[108:109], v[108:109], v[162:163] op_sel_hi:[1,0]
	v_pk_mul_f32 v[102:103], v[102:103], v[162:163] op_sel_hi:[1,0]
	v_pk_mul_f32 v[100:101], v[100:101], v[162:163] op_sel_hi:[1,0]
	v_pk_mul_f32 v[164:165], v[86:87], v[162:163] op_sel_hi:[1,0]
	v_pk_mul_f32 v[166:167], v[84:85], v[162:163] op_sel_hi:[1,0]
	v_pk_mul_f32 v[168:169], v[82:83], v[162:163] op_sel_hi:[1,0]
	v_pk_mul_f32 v[162:163], v[80:81], v[162:163] op_sel_hi:[1,0]
	v_cvt_pk_bf16_f32 v80, v124, v125
	v_cvt_pk_bf16_f32 v81, v126, v127
	v_cvt_pk_bf16_f32 v82, v120, v121
	v_cvt_pk_bf16_f32 v83, v122, v123
	v_cvt_pk_bf16_f32 v84, v104, v105
	v_cvt_pk_bf16_f32 v85, v106, v107
	v_cvt_pk_bf16_f32 v86, v96, v97
	v_cvt_pk_bf16_f32 v87, v98, v99
	v_cvt_pk_bf16_f32 v88, v116, v117
	v_cvt_pk_bf16_f32 v89, v118, v119
	v_cvt_pk_bf16_f32 v90, v112, v113
	v_cvt_pk_bf16_f32 v91, v114, v115
	v_cvt_pk_bf16_f32 v92, v92, v93
	v_cvt_pk_bf16_f32 v93, v94, v95
	v_cvt_pk_bf16_f32 v94, v160, v161
	v_cvt_pk_bf16_f32 v95, v158, v159
	v_cvt_pk_bf16_f32 v96, v108, v109
	v_cvt_pk_bf16_f32 v97, v110, v111
	v_cvt_pk_bf16_f32 v98, v100, v101
	v_cvt_pk_bf16_f32 v99, v102, v103
	flat_store_dwordx4 v[152:153], v[80:83]
	flat_store_dwordx4 v[152:153], v[84:87] offset:256
	flat_store_dwordx4 v[154:155], v[88:91]
	flat_store_dwordx4 v[154:155], v[92:95] offset:256
	flat_store_dwordx4 v[156:157], v[96:99]
	v_rsq_f32_e32 v80, v141
	v_or_b32_e32 v81, 48, v140
	v_cvt_pk_bf16_f32 v100, v166, v167
	v_cvt_pk_bf16_f32 v101, v164, v165
	v_pk_mul_f32 v[76:77], v[76:77], v[80:81] op_sel_hi:[1,0]
	v_pk_mul_f32 v[78:79], v[78:79], v[80:81] op_sel_hi:[1,0]
	v_pk_mul_f32 v[82:83], v[74:75], v[80:81] op_sel_hi:[1,0]
	v_pk_mul_f32 v[74:75], v[72:73], v[80:81] op_sel_hi:[1,0]
	v_cvt_pk_bf16_f32 v72, v76, v77
	v_mad_i64_i32 v[76:77], s[4:5], v81, s94, v[142:143]
	v_cvt_pk_bf16_f32 v73, v78, v79
	v_cvt_pk_bf16_f32 v74, v74, v75
	v_cvt_pk_bf16_f32 v75, v82, v83
	v_lshl_add_u64 v[76:77], v[76:77], 0, v[144:145]
	v_pk_mul_f32 v[68:69], v[68:69], v[80:81] op_sel_hi:[1,0]
	flat_store_dwordx4 v[76:77], v[72:75]
	v_pk_mul_f32 v[70:71], v[70:71], v[80:81] op_sel_hi:[1,0]
	v_cvt_pk_bf16_f32 v102, v162, v163
	v_pk_mul_f32 v[72:73], v[66:67], v[80:81] op_sel_hi:[1,0]
	v_pk_mul_f32 v[66:67], v[64:65], v[80:81] op_sel_hi:[1,0]
	v_cvt_pk_bf16_f32 v64, v68, v69
	v_fmamk_f32 v68, v232, 0x3b800000, v150
	v_rsq_f32_e32 v68, v68
	v_cvt_pk_bf16_f32 v65, v70, v71
	v_cvt_pk_bf16_f32 v66, v66, v67
	v_cvt_pk_bf16_f32 v67, v72, v73
	v_pk_mul_f32 v[60:61], v[60:61], v[68:69] op_sel_hi:[1,0]
; __device__ __forceinline__ u32x4 pack8(f32x4 a, f32x4 b) { u32x4 w; w.x = pk2(a[0], a[1]); w.y = pk2(a[2], a[3]); w.z = pk2(b[0], b[1]); w.w = pk2(b[2], b[3]); return w; }
;     __device__ __forceinline__ void operator()(const Acc& acc, const pg8::Unit& u, int wid) const {
;     ...
;         for (int i = 0; i < 8; ++i) scv[i] = ssq ? ssq[row0 + (i >> 2) * 128 + (i & 3) * 16] : 0.f;
;     ...
;         for (int ai = 0; ai < 2; ++ai)
; #pragma unroll
;             for (int m = 0; m < 4; ++m) {
;                 const int row = row0 + ai * 128 + m * 16;
;                 const float sc = ssq ? __builtin_amdgcn_rsqf(scv[ai * 4 + m] * inv_n + EPS) : 1.f;
; #pragma unroll
;                 for (int bj = 0; bj < 2; ++bj) {
;                     f32x4 v0 = acc[ai][bj][m][0] * sc, v1 = acc[ai][bj][m][1] * sc;
;                     if (ACT == 1) {
; #pragma unroll
;                         for (int e = 0; e < 4; ++e) { float a = fmaxf(v0[e], 0.f), b = fmaxf(v1[e], 0.f); v0[e] = a * a; v1[e] = b * b; }
;                     }
;                     *(u32x4*)(O + (size_t)row * ldc + col0 + bj * 128) = pack8(v0, v1);
	flat_store_dwordx4 v[76:77], v[64:67] offset:256
	v_pk_mul_f32 v[62:63], v[62:63], v[68:69] op_sel_hi:[1,0]
	v_pk_mul_f32 v[48:49], v[48:49], v[68:69] op_sel_hi:[1,0]
	v_pk_mul_f32 v[64:65], v[58:59], v[68:69] op_sel_hi:[1,0]
	v_pk_mul_f32 v[58:59], v[56:57], v[68:69] op_sel_hi:[1,0]
	v_cvt_pk_bf16_f32 v56, v60, v61
	v_mad_i64_i32 v[60:61], s[4:5], v170, s94, v[142:143]
	v_cvt_pk_bf16_f32 v57, v62, v63
	v_cvt_pk_bf16_f32 v58, v58, v59
	v_cvt_pk_bf16_f32 v59, v64, v65
	v_lshl_add_u64 v[60:61], v[60:61], 0, v[144:145]
	flat_store_dwordx4 v[60:61], v[56:59]
	v_pk_mul_f32 v[50:51], v[50:51], v[68:69] op_sel_hi:[1,0]
	v_cvt_pk_bf16_f32 v103, v168, v169
	v_pk_mul_f32 v[56:57], v[42:43], v[68:69] op_sel_hi:[1,0]
	v_pk_mul_f32 v[42:43], v[40:41], v[68:69] op_sel_hi:[1,0]
	v_cvt_pk_bf16_f32 v40, v48, v49
	v_cvt_pk_bf16_f32 v42, v42, v43
	v_fmamk_f32 v43, v233, 0x3b800000, v150
	v_rsq_f32_e32 v48, v43
	v_cvt_pk_bf16_f32 v41, v50, v51
	v_cvt_pk_bf16_f32 v43, v56, v57
	v_add_u32_e32 v49, 0x90, v140
	flat_store_dwordx4 v[60:61], v[40:43] offset:256
	v_pk_mul_f32 v[44:45], v[44:45], v[48:49] op_sel_hi:[1,0]
	v_pk_mul_f32 v[46:47], v[46:47], v[48:49] op_sel_hi:[1,0]
	v_pk_mul_f32 v[42:43], v[54:55], v[48:49] op_sel_hi:[1,0]
	v_pk_mul_f32 v[40:41], v[52:53], v[48:49] op_sel_hi:[1,0]
	v_pk_mul_f32 v[32:33], v[32:33], v[48:49] op_sel_hi:[1,0]
	v_cvt_pk_bf16_f32 v40, v40, v41
	v_cvt_pk_bf16_f32 v41, v42, v43
	v_cvt_pk_bf16_f32 v42, v44, v45
	v_mad_i64_i32 v[44:45], s[4:5], v49, s94, v[142:143]
	v_cvt_pk_bf16_f32 v43, v46, v47
	v_lshl_add_u64 v[44:45], v[44:45], 0, v[144:145]
	flat_store_dwordx4 v[44:45], v[40:43]
	v_pk_mul_f32 v[34:35], v[34:35], v[48:49] op_sel_hi:[1,0]
	flat_store_dwordx4 v[156:157], v[100:103] offset:256
	v_pk_mul_f32 v[40:41], v[26:27], v[48:49] op_sel_hi:[1,0]
	v_pk_mul_f32 v[26:27], v[24:25], v[48:49] op_sel_hi:[1,0]
	v_cvt_pk_bf16_f32 v24, v32, v33
	v_cvt_pk_bf16_f32 v26, v26, v27
	v_fmamk_f32 v27, v234, 0x3b800000, v150
	v_rsq_f32_e32 v32, v27
	v_cvt_pk_bf16_f32 v25, v34, v35
	v_cvt_pk_bf16_f32 v27, v40, v41
	v_add_u32_e32 v33, 0xa0, v140
	flat_store_dwordx4 v[44:45], v[24:27] offset:256
	v_pk_mul_f32 v[28:29], v[28:29], v[32:33] op_sel_hi:[1,0]
	v_pk_mul_f32 v[30:31], v[30:31], v[32:33] op_sel_hi:[1,0]
	v_pk_mul_f32 v[26:27], v[38:39], v[32:33] op_sel_hi:[1,0]
	v_pk_mul_f32 v[24:25], v[36:37], v[32:33] op_sel_hi:[1,0]
	v_pk_mul_f32 v[16:17], v[16:17], v[32:33] op_sel_hi:[1,0]
	v_cvt_pk_bf16_f32 v24, v24, v25
	v_cvt_pk_bf16_f32 v25, v26, v27
	v_cvt_pk_bf16_f32 v26, v28, v29
	v_mad_i64_i32 v[28:29], s[4:5], v33, s94, v[142:143]
	v_cvt_pk_bf16_f32 v27, v30, v31
	v_lshl_add_u64 v[28:29], v[28:29], 0, v[144:145]
	flat_store_dwordx4 v[28:29], v[24:27]
	v_pk_mul_f32 v[18:19], v[18:19], v[32:33] op_sel_hi:[1,0]
	s_nop 0
	v_pk_mul_f32 v[24:25], v[10:11], v[32:33] op_sel_hi:[1,0]
	v_pk_mul_f32 v[10:11], v[8:9], v[32:33] op_sel_hi:[1,0]
	v_cvt_pk_bf16_f32 v8, v16, v17
	v_cvt_pk_bf16_f32 v10, v10, v11
	v_fmamk_f32 v11, v235, 0x3b800000, v150
	s_min_u32 s4, s95, 0x7f
	s_lshl_b32 s4, s4, 8
	s_add_i32 s4, s4, s83
	v_mbcnt_lo_u32_b32 v238, -1, 0
	v_mbcnt_hi_u32_b32 v238, -1, v238
	v_and_or_b32 v238, v238, 15, s4
	v_ashrrev_i32_e32 v239, 31, v238
	v_lshl_add_u64 v[238:239], v[238:239], 2, s[60:61]
	global_load_dword v228, v[238:239], off
	global_load_dword v229, v[238:239], off offset:64
	global_load_dword v230, v[238:239], off offset:128
	global_load_dword v231, v[238:239], off offset:192
	global_load_dword v232, v[238:239], off offset:512
	global_load_dword v233, v[238:239], off offset:576
	global_load_dword v234, v[238:239], off offset:640
	global_load_dword v235, v[238:239], off offset:704
	v_rsq_f32_e32 v16, v11
	v_cvt_pk_bf16_f32 v9, v18, v19
	v_cvt_pk_bf16_f32 v11, v24, v25
	v_add_u32_e32 v17, 0xb0, v140
	flat_store_dwordx4 v[28:29], v[8:11] offset:256
	v_pk_mul_f32 v[12:13], v[12:13], v[16:17] op_sel_hi:[1,0]
	v_pk_mul_f32 v[14:15], v[14:15], v[16:17] op_sel_hi:[1,0]
	v_pk_mul_f32 v[10:11], v[22:23], v[16:17] op_sel_hi:[1,0]
	v_pk_mul_f32 v[8:9], v[20:21], v[16:17] op_sel_hi:[1,0]
	v_pk_mul_f32 v[6:7], v[6:7], v[16:17] op_sel_hi:[1,0]
	v_cvt_pk_bf16_f32 v8, v8, v9
	v_cvt_pk_bf16_f32 v9, v10, v11
	v_cvt_pk_bf16_f32 v10, v12, v13
	v_mad_i64_i32 v[12:13], s[4:5], v17, s94, v[142:143]
	v_cvt_pk_bf16_f32 v11, v14, v15
	v_lshl_add_u64 v[12:13], v[12:13], 0, v[144:145]
	flat_store_dwordx4 v[12:13], v[8:11]
	v_pk_mul_f32 v[4:5], v[4:5], v[16:17] op_sel_hi:[1,0]
	s_nop 0
	v_pk_mul_f32 v[8:9], v[2:3], v[16:17] op_sel_hi:[1,0]
	v_pk_mul_f32 v[2:3], v[0:1], v[16:17] op_sel_hi:[1,0]
	v_cvt_pk_bf16_f32 v0, v4, v5
	v_cvt_pk_bf16_f32 v1, v6, v7
	v_cvt_pk_bf16_f32 v2, v2, v3
	v_cvt_pk_bf16_f32 v3, v8, v9
	flat_store_dwordx4 v[12:13], v[0:3] offset:256
	s_cbranch_vccnz .LBB0_883
	s_andn2_b64 vcc, exec, s[0:1]
	s_cbranch_vccnz .LBB0_882
	s_barrier
	s_branch .LBB0_882
